# combo4 + out-proj mixer-scale table loads issued together and reused across units + second weight item's gain loads issued before the first item's stores (waits allow those stores in flight)
# speedup vs baseline: 1.0046x; 1.0017x over previous
; __device__ __forceinline__ void witem_finish(const WItem& d, f32x4 (&v)[8]) {
;     if (d.kg) { const f32x4 g0 = *(const f32x4*)(d.kg), g1 = *(const f32x4*)(d.kg + 4);
; template <int MODE> ...
;     ...
;     if (MODE != 2) { if (whA) witem_finish(wiA, wva); if (whB) witem_finish(wiB, wvb); }
.LBB0_299:
	s_andn2_b64 vcc, exec, s[22:23]
	s_cbranch_vccnz .Lwk_skip_0
	v_cmp_ne_u64_e32 vcc, 0, v[168:169]
	s_and_saveexec_b64 s[4:5], vcc
	global_load_dwordx4 v[50:53], v[168:169], off
	global_load_dwordx4 v[54:57], v[168:169], off offset:16
	s_mov_b64 exec, s[4:5]

; __device__ __forceinline__ unsigned pk_bf16(float lo, float hi) { return pg8::cvt_pk_bf16(lo, hi); }
; __device__ __forceinline__ void witem_finish(const WItem& d, f32x4 (&v)[8]) {
;     if (d.kg) { const f32x4 g0 = *(const f32x4*)(d.kg), g1 = *(const f32x4*)(d.kg + 4);
; #pragma unroll
;         for (int t = 0; t < 4; ++t) { v[t] = v[t] * g0[t]; v[4 + t] = v[4 + t] * g1[t]; } }
; #pragma unroll
;     for (int j = 0; j < 4; ++j) { u32x4 o; o.x = pk_bf16(v[0][j], v[1][j]); o.y = pk_bf16(v[2][j], v[3][j]); o.z = pk_bf16(v[4][j], v[5][j]); o.w = pk_bf16(v[6][j], v[7][j]);
;         __builtin_nontemporal_store(o, (u32x4*)(d.dst + (size_t)j * d.K)); }
.LBB0_303:
	s_andn2_b64 vcc, exec, s[22:23]
	s_cbranch_vccnz .LBB0_307
	v_cmp_ne_u64_e32 vcc, 0, v[168:169]
	s_and_saveexec_b64 s[4:5], vcc
	s_xor_b64 s[20:21], exec, s[4:5]
	s_cbranch_execz .LBB0_306
	s_waitcnt vmcnt(4)
	v_mov_b32_e32 v34, v50
	v_mov_b32_e32 v35, v51
	v_mov_b32_e32 v36, v52
	v_mov_b32_e32 v37, v53
	v_mov_b32_e32 v38, v54
	v_mov_b32_e32 v39, v55
	v_mov_b32_e32 v40, v56
	v_mov_b32_e32 v41, v57
	v_pk_mul_f32 v[122:123], v[122:123], v[34:35] op_sel_hi:[1,0]
	v_pk_mul_f32 v[120:121], v[120:121], v[34:35] op_sel_hi:[1,0]
	v_pk_mul_f32 v[126:127], v[126:127], v[34:35] op_sel:[0,1]
	v_pk_mul_f32 v[124:125], v[124:125], v[34:35] op_sel:[0,1]
	v_mov_b32_e32 v32, v37
	v_mov_b32_e32 v34, v41
	v_pk_mul_f32 v[140:141], v[140:141], v[38:39] op_sel_hi:[1,0]
	v_pk_mul_f32 v[138:139], v[138:139], v[38:39] op_sel_hi:[1,0]
	v_pk_mul_f32 v[144:145], v[144:145], v[38:39] op_sel:[0,1]
	v_pk_mul_f32 v[142:143], v[142:143], v[38:39] op_sel:[0,1]
	v_pk_mul_f32 v[132:133], v[132:133], v[36:37] op_sel_hi:[1,0]
	v_pk_mul_f32 v[130:131], v[130:131], v[36:37] op_sel_hi:[1,0]
	v_pk_mul_f32 v[148:149], v[148:149], v[40:41] op_sel_hi:[1,0]
	v_pk_mul_f32 v[146:147], v[146:147], v[40:41] op_sel_hi:[1,0]
	v_pk_mul_f32 v[136:137], v[136:137], v[32:33] op_sel_hi:[1,0]
	v_pk_mul_f32 v[134:135], v[134:135], v[32:33] op_sel_hi:[1,0]
	v_pk_mul_f32 v[152:153], v[152:153], v[34:35] op_sel_hi:[1,0]
	v_pk_mul_f32 v[150:151], v[150:151], v[34:35] op_sel_hi:[1,0]
.LBB0_306:
	s_andn2_saveexec_b64 s[20:21], s[20:21]
	s_or_b64 exec, exec, s[20:21]
	s_waitcnt vmcnt(6)
	v_cvt_pk_bf16_f32 v34, v120, v124
	s_waitcnt vmcnt(4)
	v_cvt_pk_bf16_f32 v35, v130, v134
	s_waitcnt vmcnt(4)
	v_cvt_pk_bf16_f32 v36, v138, v142
	s_waitcnt vmcnt(4)
	v_cvt_pk_bf16_f32 v37, v146, v150
	s_lshl_b64 s[4:5], s[98:99], 1
	global_store_dwordx4 v[166:167], v[34:37], off nt
	v_lshl_add_u64 v[38:39], v[166:167], 0, s[4:5]
	s_nop 0
	v_cvt_pk_bf16_f32 v34, v121, v125
	v_cvt_pk_bf16_f32 v35, v131, v135
	v_cvt_pk_bf16_f32 v36, v139, v143
	v_cvt_pk_bf16_f32 v37, v147, v151
	global_store_dwordx4 v[38:39], v[34:37], off nt
	v_lshl_add_u64 v[38:39], v[38:39], 0, s[4:5]
	s_nop 0
	v_cvt_pk_bf16_f32 v34, v122, v126
	v_cvt_pk_bf16_f32 v35, v132, v136
	v_cvt_pk_bf16_f32 v36, v140, v144
	v_cvt_pk_bf16_f32 v37, v148, v152
	global_store_dwordx4 v[38:39], v[34:37], off nt
	v_lshl_add_u64 v[38:39], v[38:39], 0, s[4:5]
	s_nop 0
	v_cvt_pk_bf16_f32 v34, v123, v127
	v_cvt_pk_bf16_f32 v35, v133, v137
	v_cvt_pk_bf16_f32 v36, v141, v145
	v_cvt_pk_bf16_f32 v37, v149, v153
	global_store_dwordx4 v[38:39], v[34:37], off nt

; __device__ __forceinline__ void witem_finish(const WItem& d, f32x4 (&v)[8]) {
;     if (d.kg) { const f32x4 g0 = *(const f32x4*)(d.kg), g1 = *(const f32x4*)(d.kg + 4);
; __device__ __forceinline__ void attn_b_unit(LAS unsigned char* lds, const bf16_t* proj, const bf16_t* vt, bf16_t* obuf, int b, int hk, int blk, const float* btab, unsigned long long* sg, bool build_lut, CP WP, int wlayer, int wbase) {
;     ...
;     if (whA) witem_finish(wiA, wva);
;     if (whB) witem_finish(wiB, wvb);
.LBB0_383:
	s_andn2_b64 vcc, exec, s[96:97]
	s_cbranch_vccnz .Lwk_skip_1
	v_cmp_ne_u64_e32 vcc, 0, v[152:153]
	s_and_saveexec_b64 s[4:5], vcc
	global_load_dwordx4 v[50:53], v[152:153], off
	global_load_dwordx4 v[54:57], v[152:153], off offset:16
	s_mov_b64 exec, s[4:5]

; __device__ __forceinline__ unsigned pk_bf16(float lo, float hi) { return pg8::cvt_pk_bf16(lo, hi); }
; __device__ __forceinline__ void witem_finish(const WItem& d, f32x4 (&v)[8]) {
;     if (d.kg) { const f32x4 g0 = *(const f32x4*)(d.kg), g1 = *(const f32x4*)(d.kg + 4);
; #pragma unroll
;         for (int t = 0; t < 4; ++t) { v[t] = v[t] * g0[t]; v[4 + t] = v[4 + t] * g1[t]; } }
; #pragma unroll
;     for (int j = 0; j < 4; ++j) { u32x4 o; o.x = pk_bf16(v[0][j], v[1][j]); o.y = pk_bf16(v[2][j], v[3][j]); o.z = pk_bf16(v[4][j], v[5][j]); o.w = pk_bf16(v[6][j], v[7][j]);
;         __builtin_nontemporal_store(o, (u32x4*)(d.dst + (size_t)j * d.K)); }
.LBB0_387:
	s_andn2_b64 vcc, exec, s[96:97]
	s_cbranch_vccnz .LBB0_391
	v_cmp_ne_u64_e32 vcc, 0, v[152:153]
	s_and_saveexec_b64 s[4:5], vcc
	s_xor_b64 s[6:7], exec, s[4:5]
	s_cbranch_execz .LBB0_390
	s_waitcnt vmcnt(4)
	v_mov_b32_e32 v32, v50
	v_mov_b32_e32 v33, v51
	v_mov_b32_e32 v34, v52
	v_mov_b32_e32 v35, v53
	v_mov_b32_e32 v36, v54
	v_mov_b32_e32 v37, v55
	v_mov_b32_e32 v38, v56
	v_mov_b32_e32 v39, v57
	v_pk_mul_f32 v[106:107], v[106:107], v[32:33] op_sel_hi:[1,0]
	v_pk_mul_f32 v[104:105], v[104:105], v[32:33] op_sel_hi:[1,0]
	v_pk_mul_f32 v[110:111], v[110:111], v[32:33] op_sel:[0,1]
	v_pk_mul_f32 v[108:109], v[108:109], v[32:33] op_sel:[0,1]
	v_pk_mul_f32 v[114:115], v[114:115], v[34:35] op_sel_hi:[1,0]
	v_pk_mul_f32 v[112:113], v[112:113], v[34:35] op_sel_hi:[1,0]
	v_mov_b32_e32 v32, v35
	v_mov_b32_e32 v34, v39
	v_pk_mul_f32 v[122:123], v[122:123], v[36:37] op_sel_hi:[1,0]
	v_pk_mul_f32 v[120:121], v[120:121], v[36:37] op_sel_hi:[1,0]
	v_pk_mul_f32 v[126:127], v[126:127], v[36:37] op_sel:[0,1]
	v_pk_mul_f32 v[124:125], v[124:125], v[36:37] op_sel:[0,1]
	v_pk_mul_f32 v[132:133], v[132:133], v[38:39] op_sel_hi:[1,0]
	v_pk_mul_f32 v[130:131], v[130:131], v[38:39] op_sel_hi:[1,0]
	v_pk_mul_f32 v[118:119], v[118:119], v[32:33] op_sel_hi:[1,0]
	v_pk_mul_f32 v[116:117], v[116:117], v[32:33] op_sel_hi:[1,0]
	v_pk_mul_f32 v[136:137], v[136:137], v[34:35] op_sel_hi:[1,0]
	v_pk_mul_f32 v[134:135], v[134:135], v[34:35] op_sel_hi:[1,0]
.LBB0_390:
	s_andn2_saveexec_b64 s[6:7], s[6:7]
	s_or_b64 exec, exec, s[6:7]
	s_waitcnt vmcnt(6)
	v_cvt_pk_bf16_f32 v32, v104, v108
	s_waitcnt vmcnt(4)
	v_cvt_pk_bf16_f32 v33, v112, v116
	s_waitcnt vmcnt(4)
	v_cvt_pk_bf16_f32 v34, v120, v124
	s_waitcnt vmcnt(4)
	v_cvt_pk_bf16_f32 v35, v130, v134
	s_lshl_b64 s[4:5], s[94:95], 1
	global_store_dwordx4 v[150:151], v[32:35], off nt
	v_lshl_add_u64 v[36:37], v[150:151], 0, s[4:5]
	s_nop 0
	v_cvt_pk_bf16_f32 v32, v105, v109
	v_cvt_pk_bf16_f32 v33, v113, v117
	v_cvt_pk_bf16_f32 v34, v121, v125
	v_cvt_pk_bf16_f32 v35, v131, v135
	global_store_dwordx4 v[36:37], v[32:35], off nt
	v_lshl_add_u64 v[36:37], v[36:37], 0, s[4:5]
	s_nop 0
	v_cvt_pk_bf16_f32 v32, v106, v110
	v_cvt_pk_bf16_f32 v33, v114, v118
	v_cvt_pk_bf16_f32 v34, v122, v126
	v_cvt_pk_bf16_f32 v35, v132, v136
	global_store_dwordx4 v[36:37], v[32:35], off nt
	v_lshl_add_u64 v[36:37], v[36:37], 0, s[4:5]
	s_nop 0
	v_cvt_pk_bf16_f32 v32, v107, v111
	v_cvt_pk_bf16_f32 v33, v115, v119
	v_cvt_pk_bf16_f32 v34, v123, v127
	v_cvt_pk_bf16_f32 v35, v133, v137
	global_store_dwordx4 v[36:37], v[32:35], off nt

; __global__ void __launch_bounds__(512, 2) hymba_fwd(Params Parg) {
;     ...
;             {
;                 const unsigned long long* sgA = (const unsigned long long*)(ws + WS_SG) + (size_t)(3 * layer) * MTOK;
;                 pg8::Unit uu;
;                 int tb_ = threadIdx.x; asm volatile("" : "+v"(tb_));
; #pragma unroll 1
;                 for (int ui = 0; ui < 4 && S.next(ui, uu); ++ui)
.LBB0_447:
	s_or_b64 exec, exec, s[6:7]
	v_readlane_b32 s4, v250, 11
	v_readlane_b32 s5, v250, 12
	s_waitcnt lgkmcnt(0)
	s_barrier
	s_load_dwordx2 s[22:23], s[4:5], 0x88
	v_mov_b32_e32 v2, v199
	s_movk_i32 s4, 0x100
	s_nop 0
	v_cmp_gt_i32_e64 s[6:7], s4, v2
	s_waitcnt lgkmcnt(0)
	s_add_u32 s4, s22, s0
	v_ashrrev_i32_e32 v3, 31, v2
	s_addc_u32 s5, s23, s1
	v_lshl_add_u64 v[0:1], v[2:3], 3, s[4:5]
	v_readlane_b32 s4, v250, 44
	v_add_u32_e32 v4, 0xfffffe00, v2
	s_nop 0
	v_lshl_add_u32 v5, v2, 2, s4
	s_mov_b32 s4, 0
	v_mov_b32_e32 v116, 0
	v_mov_b32_e32 v117, 0
	s_branch .LBB0_450

; __global__ void __launch_bounds__(512, 2) hymba_fwd(Params Parg) {
;     ...
;                 for (int ui = 0; ui < 4 && S.next(ui, uu); ++ui)
;                     for (int rl = tb_; rl < 256; rl += 512) { const size_t tok = (size_t)uu.pm * 256 + rl;
;                         const float ra = rsqrtf((float)sgA[tok] * (1.f / (512.f * 16777216.f)) + EPS), rb = rsqrtf((float)sgA[MTOK + tok] * (1.f / (512.f * 16777216.f)) + EPS),
;                                     rc = rsqrtf((float)sgA[2 * MTOK + tok] * (1.f / (1024.f * 16777216.f)) + EPS);
;                         tab[(ui * 3 + 0) * 256 + rl] = ra / rb; tab[(ui * 3 + 1) * 256 + rl] = rb / rc; tab[(ui * 3 + 2) * 256 + rl] = rc; }
.LBB0_459:
	v_cmp_ne_u64_e32 vcc, v[2:3], v[116:117]
	s_cbranch_vccz .Lmix_reuse
	v_mov_b32_e32 v116, v2
	v_mov_b32_e32 v117, v3
	v_add_co_u32_e32 v104, vcc, 0x2b120000, v2
	s_nop 1
	v_addc_co_u32_e32 v105, vcc, 0, v3, vcc
	v_add_co_u32_e32 v106, vcc, 0x2b140000, v2
	s_nop 1
	v_addc_co_u32_e32 v107, vcc, 0, v3, vcc
	v_add_co_u32_e32 v108, vcc, 0x2b160000, v2
	s_nop 1
	v_addc_co_u32_e32 v109, vcc, 0, v3, vcc
	global_load_dwordx2 v[110:111], v[104:105], off
	global_load_dwordx2 v[112:113], v[106:107], off
	global_load_dwordx2 v[114:115], v[108:109], off
.Lmix_reuse:
	v_add_co_u32_e32 v8, vcc, 0x2b120000, v2
	s_mov_b32 s5, 0x2b140000
	s_nop 0
	v_addc_co_u32_e32 v9, vcc, 0, v3, vcc
	s_waitcnt vmcnt(2)
	v_mov_b32_e32 v8, v110
	v_mov_b32_e32 v9, v111
	v_add_u32_e32 v6, 0x200, v6
	v_ffbh_u32_e32 v10, v9
	v_min_u32_e32 v10, 32, v10
	v_lshlrev_b64 v[8:9], v10, v[8:9]
	v_min_u32_e32 v8, 1, v8
	v_or_b32_e32 v8, v9, v8
	v_cvt_f32_u32_e32 v8, v8
	v_sub_u32_e32 v9, 32, v10
	v_ldexp_f32 v8, v8, v9
	v_fmamk_f32 v8, v8, 0x2f000000, v209
	v_cmp_gt_f32_e32 vcc, s49, v8
	v_mul_f32_e32 v9, 0x4b800000, v8
	s_nop 0
	v_cndmask_b32_e32 v8, v8, v9, vcc
	v_rsq_f32_e32 v8, v8
	s_nop 0
	v_mul_f32_e32 v9, 0x45800000, v8
	v_cndmask_b32_e32 v10, v8, v9, vcc
	v_add_co_u32_e32 v8, vcc, s5, v2
	s_mov_b32 s5, 0x2b160000
	s_nop 0
	v_addc_co_u32_e32 v9, vcc, 0, v3, vcc
	s_waitcnt vmcnt(1)
	v_mov_b32_e32 v8, v112
	v_mov_b32_e32 v9, v113
	v_ffbh_u32_e32 v11, v9
	v_min_u32_e32 v11, 32, v11
	v_lshlrev_b64 v[8:9], v11, v[8:9]
	v_min_u32_e32 v8, 1, v8
	v_or_b32_e32 v8, v9, v8
	v_cvt_f32_u32_e32 v8, v8
	v_sub_u32_e32 v9, 32, v11
	v_ldexp_f32 v8, v8, v9
	v_fmamk_f32 v8, v8, 0x2f000000, v209
	v_cmp_gt_f32_e32 vcc, s49, v8
	v_mul_f32_e32 v9, 0x4b800000, v8
	s_nop 0
	v_cndmask_b32_e32 v8, v8, v9, vcc
	v_rsq_f32_e32 v8, v8
	s_nop 0
	v_mul_f32_e32 v9, 0x45800000, v8
	v_cndmask_b32_e32 v11, v8, v9, vcc
	v_add_co_u32_e32 v8, vcc, s5, v2
	s_nop 1
	v_addc_co_u32_e32 v9, vcc, 0, v3, vcc
	s_waitcnt vmcnt(0)
	v_mov_b32_e32 v8, v114
	v_mov_b32_e32 v9, v115
	v_lshl_add_u64 v[2:3], v[2:3], 0, s[62:63]
	v_ffbh_u32_e32 v12, v9
	v_min_u32_e32 v12, 32, v12
	v_lshlrev_b64 v[8:9], v12, v[8:9]
	v_min_u32_e32 v8, 1, v8
	v_or_b32_e32 v8, v9, v8
	v_cvt_f32_u32_e32 v8, v8
	v_sub_u32_e32 v9, 32, v12
	v_ldexp_f32 v8, v8, v9
	v_fmamk_f32 v8, v8, 0x2e800000, v209
	v_cmp_gt_f32_e32 vcc, s49, v8
	v_mul_f32_e32 v9, 0x4b800000, v8
	s_nop 0
	v_cndmask_b32_e32 v8, v8, v9, vcc
	v_rsq_f32_e32 v8, v8
	s_nop 0
	v_mul_f32_e32 v9, 0x45800000, v8
	v_cndmask_b32_e32 v8, v8, v9, vcc
	v_div_scale_f32 v9, s[10:11], v11, v11, v10
	v_rcp_f32_e32 v12, v9
	ds_write_b32 v7, v8 offset:2048
	v_fma_f32 v13, -v9, v12, 1.0
	v_fmac_f32_e32 v12, v13, v12
	v_div_scale_f32 v13, vcc, v10, v11, v10
	v_mul_f32_e32 v14, v13, v12
	v_fma_f32 v15, -v9, v14, v13
	v_fmac_f32_e32 v14, v15, v12
	v_fma_f32 v9, -v9, v14, v13
	v_div_fmas_f32 v9, v9, v12, v14
	v_div_fixup_f32 v9, v9, v11, v10
	v_div_scale_f32 v10, s[10:11], v8, v8, v11
	v_rcp_f32_e32 v12, v10
	s_nop 0
	v_fma_f32 v13, -v10, v12, 1.0
	v_fmac_f32_e32 v12, v13, v12
	v_div_scale_f32 v13, vcc, v11, v8, v11
	v_mul_f32_e32 v14, v13, v12
	v_fma_f32 v15, -v10, v14, v13
	v_fmac_f32_e32 v14, v15, v12
	v_fma_f32 v10, -v10, v14, v13
	v_div_fmas_f32 v10, v10, v12, v14
	v_div_fixup_f32 v10, v10, v8, v11
	ds_write2st64_b32 v7, v9, v10 offset1:4
	v_add_u32_e32 v9, 0x800, v7
	v_cmp_lt_i32_e32 vcc, s50, v6
	s_or_b64 s[12:13], vcc, s[12:13]
	v_mov_b32_e32 v7, v9
	s_andn2_b64 exec, exec, s[12:13]
	s_cbranch_execnz .LBB0_459
	s_branch .LBB0_448
